# m_out unit loop rotated: next unit's state/V loads issued in the current unit's tail (after the tail's own loads), first unit peeled into the preheader
# speedup vs baseline: 1.0023x; 1.0023x over previous
; #define LAS __attribute__((address_space(3)))
; DI float fexp(float x) { return __builtin_amdgcn_exp2f(x * LOG2E); }
; DI void phase_m_out(int wv, const ArgP a, LAS unsigned char* lds, int dry) {
;     unsigned char* ws = a.ws(); const int tid = ltid(wv), lane = tid & 63, r32 = lane & 31, hi = lane >> 5; const int w = __builtin_amdgcn_readfirstlane(tid >> 6);
;     bf16_t* QOK = (bf16_t*)(ws + O_QOK); const bf16_t* KVT = (const bf16_t*)(ws + O_KVT); const bf16_t* CST = (const bf16_t*)(ws + O_CST);
;     const float* GB = (const float*)(ws + O_GB); const float* GE = (const float*)(ws + O_GE); const float* GPM = (const float*)(ws + O_GPM);
;     const float* MST = (const float*)(ws + O_MST); const float* NST = (const float*)(ws + O_NST); const float* ong = a.in(20);
;     LAS unsigned char* Qs = lds + MC_QS; LAS unsigned char* Ks = lds + MC_KS; LAS unsigned char* Sc = lds + MC_SC;
;     LAS float* F = (LAS float*)(lds + MC_F);
;     LAS float* f_b = F, *f_e = F + 64, *f_m = F + 128, *f_g = F + 192, *f_qn = F + 256, *f_ps = F + 320  , *f_n = F + 576  , *f_part = F + 704  ;
;     for (int u = blockIdx.x; u < 1024; u += gridDim.x) {
;         const int c = u >> 2, h = u & 3; const size_t t0 = (size_t)c * 64;
;         for (int e = tid; e < 1024; e += 512) { const int r = e >> 4, p = e & 15;
;             *(LAS u32x4*)(Qs + r * MC_QROW + p * 16) = *(const u32x4*)(QOK + (t0 + r) * 2048 + h * 128 + p * 8);
;             *(LAS u32x4*)(Ks + r * MC_QROW + p * 16) = *(const u32x4*)(QOK + (t0 + r) * 2048 + 1536 + h * 128 + p * 8); }
;         if (tid < 64) { const float mstv = MST[c * 4 + h]; const float b = GB[(size_t)h * S + t0 + tid], e = GE[(size_t)h * S + t0 + tid], pm = GPM[(size_t)h * S + t0 + tid];
;             const float m = b + fmaxf(mstv, pm); f_b[tid] = b; f_e[tid] = e; f_m[tid] = m; f_g[tid] = fexp(b + mstv - m); }
;         if (tid >= 64 && tid < 192) f_n[tid - 64] = NST[(size_t)(c * 4 + h) * 128 + tid - 64];
;         __syncthreads();
;     ...
;         { const bf16_t* cp = CST + ((size_t)(c * 4 + h) * 256 + 32 * w + r32) * 128 + 8 * hi;
; #pragma unroll
;           for (int ks = 0; ks < 8; ++ks) { const bf16x8 ca = *(const bf16x8*)(cp + 16 * ks);
;               const bf16x8 q0 = *(const LAS bf16x8*)(Qs + r32 * MC_QROW + (16 * ks + 8 * hi) * 2), q1 = *(const LAS bf16x8*)(Qs + (32 + r32) * MC_QROW + (16 * ks + 8 * hi) * 2);
.LBB0_1603:
	s_or_b64 exec, exec, s[0:1]
	s_mov_b64 s[2:3], s[82:83]
	s_mov_b32 s0, s50
	s_waitcnt lgkmcnt(0)
	v_mov_b32_e32 v0, v192
	s_barrier
	s_and_b64 vcc, exec, s[6:7]
	v_lshl_add_u32 v32, s0, 6, v0
	s_nop 0
	v_readfirstlane_b32 s0, v32
	s_cbranch_vccz .LBB0_1654
	s_load_dwordx2 s[12:13], s[2:3], 0xe8
	s_load_dwordx2 s[14:15], s[2:3], 0xa0
	v_subrev_u32_e32 v2, 64, v32
	s_movk_i32 s8, 0x80
	v_mov_b32_e32 v37, 0
	s_waitcnt lgkmcnt(0)
	s_add_u32 s2, s12, 0x7e0b000
	s_addc_u32 s3, s13, 0
	s_add_u32 s50, s12, 0xbe0b000
	s_addc_u32 s51, s13, 0
	s_add_u32 s52, s12, 0x1c40000
	s_addc_u32 s53, s13, 0
	s_add_u32 s54, s12, 0x1c80000
	s_addc_u32 s55, s13, 0
	s_add_u32 s56, s12, 0x1cc0000
	s_addc_u32 s57, s13, 0
	s_add_u32 s33, s12, 0x1d02000
	s_addc_u32 s63, s13, 0
	s_ashr_i32 s18, s0, 6
	v_mov_b32_e32 v36, v32
	s_cmp_gt_i32 s18, 3
	v_cmp_gt_u32_e64 s[8:9], s8, v2
	v_lshl_add_u64 v[2:3], v[36:37], 2, s[12:13]
	s_mov_b64 s[10:11], 0x1d02f00
	s_cselect_b64 s[58:59], -1, 0
	s_lshl_b32 s16, s18, 4
	v_lshl_add_u64 v[38:39], v[2:3], 0, s[10:11]
	s_sub_i32 s10, s16, 64
	v_bfe_u32 v2, v0, 2, 4
	v_or_b32_e32 v3, s10, v2
	v_or_b32_e32 v2, s16, v2
	s_and_b32 s19, s18, 1
	s_ashr_i32 s16, s0, 2
	v_and_b32_e32 v34, 31, v0
	v_lshl_add_u32 v47, v2, 2, 0
	s_movk_i32 s17, 0xffe0
	v_mov_b32_e32 v2, s16
	s_lshl_b32 s20, s19, 5
	s_movk_i32 s72, 0x110
	v_bfi_b32 v10, s17, v2, v0
	v_or_b32_e32 v2, s20, v34
	v_mad_u32_u24 v11, v2, s72, 0
	v_mul_lo_u32 v2, v10, s72
	v_bfe_u32 v4, v0, 5, 1
	v_lshl_add_u32 v43, v32, 2, 0
	v_add_u32_e32 v42, 0, v2
	s_movk_i32 s21, 0xfef4
	v_mad_u64_u32 v[44:45], s[16:17], v10, s21, v[42:43]
	v_lshlrev_b32_e32 v2, 2, v4
	v_and_b32_e32 v1, 63, v0
	v_and_b32_e32 v8, 3, v0
	v_or_b32_e32 v12, s20, v2
	s_movk_i32 s16, 0x8c
	v_lshlrev_b32_e32 v0, 4, v0
	v_mul_lo_u32 v5, v10, s16
	s_lshl_b32 s17, s19, 6
	v_and_b32_e32 v36, 0xf0, v0
	v_or_b32_e32 v0, 2, v12
	v_add3_u32 v45, v44, v5, s17
	s_lshl_b32 s17, s19, 9
	s_lshl_b32 s60, s18, 5
	v_mad_u32_u24 v59, v34, s72, 0
	v_cmp_le_i32_e64 s[18:19], v0, v10
	v_or_b32_e32 v0, 3, v12
	v_mad_i32_i24 v68, v34, s21, v59
	v_cmp_le_i32_e64 s[20:21], v0, v10
	v_or_b32_e32 v0, 8, v12
	v_cmp_le_i32_e64 s[22:23], v0, v10
	v_or_b32_e32 v0, 9, v12
	v_cmp_le_i32_e64 s[24:25], v0, v10
	v_or_b32_e32 v0, 10, v12
	v_cmp_le_i32_e64 s[26:27], v0, v10
	v_or_b32_e32 v0, 11, v12
	v_cmp_le_i32_e64 s[28:29], v0, v10
	v_or_b32_e32 v0, 16, v12
	v_cmp_le_i32_e64 s[30:31], v0, v10
	v_or_b32_e32 v0, 17, v12
	v_cmp_le_i32_e64 s[34:35], v0, v10
	v_or_b32_e32 v0, 18, v12
	v_cmp_le_i32_e64 s[36:37], v0, v10
	v_or_b32_e32 v0, 19, v12
	v_cmp_le_i32_e64 s[38:39], v0, v10
	v_or_b32_e32 v0, 24, v12
	v_cmp_le_i32_e64 s[40:41], v0, v10
	v_or_b32_e32 v0, 25, v12
	v_lshlrev_b32_e32 v40, 4, v4
	v_lshlrev_b32_e32 v46, 3, v4
	s_add_i32 s17, s17, 0
	v_lshlrev_b32_e32 v4, 8, v4
	v_lshlrev_b32_e32 v5, 2, v10
	s_ashr_i32 s61, s60, 31
	s_load_dword s73, s[88:89], 0x0
	v_cmp_le_i32_e64 s[42:43], v0, v10
	v_or_b32_e32 v0, 26, v12
	v_add3_u32 v49, s17, v4, v5
	v_or_b32_e32 v4, s60, v34
	v_mov_b32_e32 v5, s61
	v_mov_b32_e32 v41, v37
	v_mad_u32_u24 v13, v34, s16, v68
	s_and_b32 s0, s0, 0x3fffffc0
	s_lshl_b64 s[16:17], s[60:61], 2
	v_cmp_le_i32_e64 s[44:45], v0, v10
	v_or_b32_e32 v0, 27, v12
	v_lshl_add_u32 v35, v34, 2, 0
	v_mul_lo_u32 v3, v3, s72
	v_lshl_add_u64 v[6:7], s[12:13], 0, v[40:41]
	v_cmp_gt_u32_e64 s[12:13], 32, v1
	s_add_u32 s48, s14, s16
	v_cmp_le_i32_e64 s[46:47], v0, v10
	v_lshlrev_b64 v[0:1], 8, v[4:5]
	s_movk_i32 s4, 0x400
	v_add_u32_e32 v3, 0, v3
	v_lshlrev_b32_e32 v9, 7, v8
	v_cmp_eq_u32_e64 s[10:11], 0, v8
	v_lshl_add_u32 v14, s0, 2, v35
	s_addc_u32 s49, s15, s17
	v_lshlrev_b32_e32 v8, 6, v8
	v_lshl_add_u64 v[0:1], v[6:7], 0, v[0:1]
	s_mov_b64 s[64:65], 0x3e0b000
	s_mov_b32 s1, 0
	v_cmp_gt_i32_e64 s[4:5], s4, v32
	v_cmp_gt_i32_e64 s[6:7], 64, v32
	v_ashrrev_i32_e32 v33, 31, v32
	v_add_u32_e32 v69, 0x200, v4
	v_add_u32_e32 v48, 0, v36
	v_cmp_le_i32_e64 s[14:15], v12, v10
	v_lshl_add_u32 v70, v12, 2, 0
	v_cmp_lt_i32_e64 s[16:17], v12, v10
	v_lshl_add_u64 v[50:51], v[0:1], 0, s[64:65]
	v_lshl_add_u64 v[52:53], s[2:3], 0, v[36:37]
	v_lshl_add_u64 v[54:55], s[48:49], 0, v[40:41]
	s_movk_i32 s74, 0x1ff
	v_add_u32_e32 v41, v3, v8
	v_add_u32_e32 v71, 0, v9
	v_add_u32_e32 v72, v11, v40
	v_lshlrev_b32_e32 v36, 1, v46
	v_add_u32_e32 v73, v13, v40
	s_mov_b32 s62, 0x3b800000
	s_mov_b32 s75, 0x800000
	v_lshlrev_b32_e32 v56, 1, v2
	s_mov_b64 s[64:65], 0x20400
	v_add_u32_e32 v74, 0xb400, v14
	v_mov_b32_e32 v58, 0x358637bd
	s_mov_b32 s66, s80
	s_ashr_i32 s48, s66, 2
	s_ashr_i32 s49, s48, 31
	s_and_b32 s76, s66, 3
	s_lshl_b64 s[68:69], s[48:49], 6
	s_ashr_i32 s99, s66, 31
	s_mov_b32 s98, s66
	s_lshl_b64 s[98:99], s[98:99], 16
	v_lshl_add_u64 v[188:189], v[50:51], 0, s[98:99]
	global_load_dwordx4 v[140:143], v[188:189], off
	global_load_dwordx4 v[144:147], v[188:189], off offset:32
	global_load_dwordx4 v[148:151], v[188:189], off offset:64
	global_load_dwordx4 v[152:155], v[188:189], off offset:96
	global_load_dwordx4 v[156:159], v[188:189], off offset:128
	global_load_dwordx4 v[160:163], v[188:189], off offset:160
	global_load_dwordx4 v[164:167], v[188:189], off offset:192
	global_load_dwordx4 v[168:171], v[188:189], off offset:224
	s_lshl_b32 s98, s76, 8
	v_add_u32_e32 v190, s98, v69
	v_ashrrev_i32_e32 v191, 31, v190
	v_lshlrev_b64 v[190:191], 15, v[190:191]
	v_lshl_add_u64 v[190:191], s[50:51], 0, v[190:191]
	v_lshl_add_u64 v[190:191], s[68:69], 1, v[190:191]
	v_lshl_add_u64 v[190:191], v[190:191], 0, v[36:37]
	global_load_dwordx4 v[172:175], v[190:191], off
	global_load_dwordx4 v[176:179], v[190:191], off offset:32
	global_load_dwordx4 v[180:183], v[190:191], off offset:64
	global_load_dwordx4 v[184:187], v[190:191], off offset:96
	s_branch .LBB0_1606
; DI unsigned pk2(float lo, float hi) { f32x2 v = {lo, hi}; bf16x2_t b = __builtin_convertvector(v, bf16x2_t); return __builtin_bit_cast(unsigned, b); }
; DI float bflo(unsigned u) { return __uint_as_float(u << 16); }
; DI float bfhi(unsigned u) { return __uint_as_float(u & 0xffff0000u); }
; DI void phase_m_out(int wv, const ArgP a, LAS unsigned char* lds, int dry) {
;     ...
;         float inv[2];
; #pragma unroll
;         for (int tb = 0; tb < 2; ++tb) { const int tl = 32 * tb + r32;
;             const float den = f_g[tl] * f_qn[tl] + f_ps[tl] + f_ps[64 + tl] + f_ps[128 + tl] + f_ps[192 + tl];
;             inv[tb] = 1.f / fmaxf(fabsf(den), fexp(-f_m[tl])); }
;         float ss0 = 0.f, ss1 = 0.f;
; #pragma unroll
;         for (int r = 0; r < 16; ++r) { acc0[r] *= inv[0]; acc1[r] *= inv[1]; ss0 += acc0[r] * acc0[r]; ss1 += acc1[r] * acc1[r]; }
;         ss0 += __shfl_xor(ss0, 32); ss1 += __shfl_xor(ss1, 32);
;         if (hi == 0) { f_part[w * 64 + r32] = ss0; f_part[w * 64 + 32 + r32] = ss1; }
;         __syncthreads();
;         float rn[2];
; #pragma unroll
;         for (int tb = 0; tb < 2; ++tb) { float s = 0.f;
; #pragma unroll
;             for (int ww = 0; ww < 8; ++ww) s += f_part[ww * 64 + 32 * tb + r32];
;             rn[tb] = rsqrtf(s * (1.f / 256.f) + EPS); }
; #pragma unroll
;         for (int tb = 0; tb < 2; ++tb) { bf16_t* op = QOK + (t0 + 32 * tb + r32) * 2048 + 512 + h * 256 + 32 * w;
; #pragma unroll
;             for (int p = 0; p < 2; ++p) {
;                 unsigned pk[2][2];
; #pragma unroll
;                 for (int q = 0; q < 2; ++q) { const int g = 2 * p + q, dv = 8 * g + 4 * hi; const u32x2 ov = *(const u32x2*)(op + dv);
;                     const f32x4 gg = *(const f32x4*)(ong + h * 256 + 32 * w + dv);
;                     const float og[4] = {bflo(ov.x), bfhi(ov.x), bflo(ov.y), bfhi(ov.y)}; float y[4];
; #pragma unroll
;                     for (int j = 0; j < 4; ++j) { const float hv = (tb ? acc1[4 * g + j] : acc0[4 * g + j]) * rn[tb]; y[j] = hv * gg[j] * sigmoidf_(og[j]); }
;                     pk[q][0] = pk2(y[0], y[1]); pk[q][1] = pk2(y[2], y[3]); }
;                 const auto r0 = __builtin_amdgcn_permlane32_swap(pk[0][0], pk[1][0], false, false), r1 = __builtin_amdgcn_permlane32_swap(pk[0][1], pk[1][1], false, false);
;                 if (!dry) *(u32x4*)(op + 16 * p + 8 * hi) = (u32x4){r0[0], r1[0], r0[1], r1[1]}; } }
.LBB0_1605:
	s_or_b64 exec, exec, s[48:49]
	v_mov_b32_e32 v9, s69
	v_or_b32_e32 v8, s68, v34
	v_lshlrev_b64 v[8:9], 12, v[8:9]
	v_lshl_add_u64 v[8:9], s[2:3], 0, v[8:9]
	s_lshl_b32 s0, s67, 1
	v_lshl_add_u64 v[8:9], v[8:9], 0, s[0:1]
	s_lshl_b32 s0, s67, 2
	v_lshl_add_u64 v[30:31], s[60:61], 1, v[8:9]
	v_mov_b32_e32 v57, v37
	v_lshl_add_u64 v[8:9], v[54:55], 0, s[0:1]
	s_waitcnt lgkmcnt(0)
	s_barrier
	v_lshl_add_u64 v[188:189], v[30:31], 0, v[56:57]
	v_lshl_add_u64 v[190:191], v[30:31], 0, s[64:65]
	v_lshl_add_u64 v[190:191], v[190:191], 0, v[56:57]
	global_load_dwordx4 v[104:107], v[8:9], off
	global_load_dwordx2 v[108:109], v[188:189], off offset:1024
	global_load_dwordx2 v[110:111], v[188:189], off offset:1040
	global_load_dwordx4 v[112:115], v[8:9], off offset:32
	global_load_dwordx2 v[116:117], v[188:189], off offset:1056
	global_load_dwordx2 v[118:119], v[188:189], off offset:1072
	global_load_dwordx4 v[120:123], v[8:9], off offset:64
	global_load_dwordx4 v[124:127], v[8:9], off offset:96
	global_load_dwordx2 v[128:129], v[190:191], off
	global_load_dwordx2 v[130:131], v[190:191], off offset:16
	global_load_dwordx2 v[132:133], v[190:191], off offset:32
	global_load_dwordx2 v[134:135], v[190:191], off offset:48
	s_add_i32 s66, s66, s73
	s_sub_i32 s85, s66, s73
	s_cmpk_lt_i32 s66, 0x400
	s_cselect_b32 s84, s66, s85
	s_ashr_i32 s48, s84, 2
	s_ashr_i32 s49, s48, 31
	s_and_b32 s76, s84, 3
	s_lshl_b64 s[68:69], s[48:49], 6
	s_ashr_i32 s99, s84, 31
	s_mov_b32 s98, s84
	s_lshl_b64 s[98:99], s[98:99], 16
	v_lshl_add_u64 v[188:189], v[50:51], 0, s[98:99]
	global_load_dwordx4 v[140:143], v[188:189], off
	global_load_dwordx4 v[144:147], v[188:189], off offset:32
	global_load_dwordx4 v[148:151], v[188:189], off offset:64
	global_load_dwordx4 v[152:155], v[188:189], off offset:96
	global_load_dwordx4 v[156:159], v[188:189], off offset:128
	global_load_dwordx4 v[160:163], v[188:189], off offset:160
	global_load_dwordx4 v[164:167], v[188:189], off offset:192
	global_load_dwordx4 v[168:171], v[188:189], off offset:224
	s_lshl_b32 s98, s76, 8
	v_add_u32_e32 v190, s98, v69
	v_ashrrev_i32_e32 v191, 31, v190
	v_lshlrev_b64 v[190:191], 15, v[190:191]
	v_lshl_add_u64 v[190:191], s[50:51], 0, v[190:191]
	v_lshl_add_u64 v[190:191], s[68:69], 1, v[190:191]
	v_lshl_add_u64 v[190:191], v[190:191], 0, v[36:37]
	global_load_dwordx4 v[172:175], v[190:191], off
	global_load_dwordx4 v[176:179], v[190:191], off offset:32
	global_load_dwordx4 v[180:183], v[190:191], off offset:64
	global_load_dwordx4 v[184:187], v[190:191], off offset:96
	v_lshl_add_u64 v[84:85], v[30:31], 0, v[56:57]
	ds_read2_b32 v[14:15], v75 offset0:192 offset1:224
	v_add_u32_e32 v75, 0xb800, v35
	v_add_u32_e32 v80, 0xbc00, v35
	ds_read2_b32 v[28:29], v75 offset1:32
	ds_read2_b32 v[90:91], v75 offset0:64 offset1:96
	ds_read2_b32 v[92:93], v75 offset0:128 offset1:160
	ds_read2_b32 v[94:95], v75 offset0:192 offset1:224
	ds_read2_b32 v[96:97], v80 offset1:32
	ds_read2_b32 v[98:99], v80 offset0:64 offset1:96
	ds_read2_b32 v[100:101], v80 offset0:128 offset1:160
	s_waitcnt lgkmcnt(7)
	v_mov_b32_e32 v102, v15
	v_mov_b32_e32 v103, v14
	v_pk_add_f32 v[14:15], v[102:103], 0 op_sel_hi:[1,0]
	s_waitcnt lgkmcnt(6)
	v_mov_b32_e32 v102, v29
	v_mov_b32_e32 v103, v28
	s_waitcnt lgkmcnt(5)
	v_mov_b32_e32 v28, v91
	v_mov_b32_e32 v29, v90
	v_pk_add_f32 v[14:15], v[14:15], v[102:103]
	s_waitcnt lgkmcnt(4)
	v_mov_b32_e32 v90, v93
	v_mov_b32_e32 v91, v92
	v_pk_add_f32 v[14:15], v[14:15], v[28:29]
	s_waitcnt lgkmcnt(3)
	v_mov_b32_e32 v92, v95
	v_mov_b32_e32 v93, v94
	v_pk_add_f32 v[14:15], v[14:15], v[90:91]
	s_waitcnt lgkmcnt(2)
	v_mov_b32_e32 v94, v97
	v_mov_b32_e32 v95, v96
	v_pk_add_f32 v[14:15], v[14:15], v[92:93]
	s_waitcnt lgkmcnt(1)
	v_mov_b32_e32 v96, v99
	v_mov_b32_e32 v97, v98
	v_pk_add_f32 v[14:15], v[14:15], v[94:95]
	s_waitcnt lgkmcnt(0)
	v_mov_b32_e32 v98, v101
	v_mov_b32_e32 v99, v100
	v_pk_add_f32 v[14:15], v[14:15], v[96:97]
	s_nop 0
	v_pk_add_f32 v[14:15], v[14:15], v[98:99]
	v_pk_fma_f32 v[14:15], v[14:15], s[62:63], v[58:59] op_sel_hi:[1,0,0]
	v_mul_f32_e32 v28, 0x4b800000, v15
	v_cmp_gt_f32_e32 vcc, s75, v15
	s_nop 1
	v_cndmask_b32_e32 v15, v15, v28, vcc
	v_rsq_f32_e32 v15, v15
	v_lshl_add_u64 v[28:29], v[30:31], 0, v[36:37]
	v_lshl_add_u64 v[30:31], v[30:31], 0, s[64:65]
	v_mul_f32_e32 v75, 0x45800000, v15
	v_cndmask_b32_e32 v92, v15, v75, vcc
	v_pk_mul_f32 v[64:65], v[64:65], v[92:93] op_sel_hi:[1,0]
	v_pk_mul_f32 v[66:67], v[66:67], v[92:93] op_sel_hi:[1,0]
	v_pk_mul_f32 v[62:63], v[62:63], v[92:93] op_sel_hi:[1,0]
	v_pk_mul_f32 v[60:61], v[60:61], v[92:93] op_sel_hi:[1,0]
	v_pk_mul_f32 v[24:25], v[24:25], v[92:93] op_sel_hi:[1,0]
	v_pk_mul_f32 v[26:27], v[26:27], v[92:93] op_sel_hi:[1,0]
	v_pk_mul_f32 v[10:11], v[10:11], v[92:93] op_sel_hi:[1,0]
	v_pk_mul_f32 v[12:13], v[12:13], v[92:93] op_sel_hi:[1,0]
	v_cmp_gt_f32_e32 vcc, s75, v14
	s_waitcnt vmcnt(23)
	v_pk_mul_f32 v[64:65], v[64:65], v[104:105]
	s_waitcnt vmcnt(22)
	v_lshlrev_b32_e32 v15, 16, v108
	v_and_b32_e32 v75, 0xffff0000, v108
	v_lshlrev_b32_e32 v76, 16, v109
	v_and_b32_e32 v77, 0xffff0000, v109
	v_mul_f32_e32 v15, 0xbfb8aa3b, v15
	v_mul_f32_e32 v75, 0xbfb8aa3b, v75
	v_mul_f32_e32 v76, 0xbfb8aa3b, v76
	v_mul_f32_e32 v77, 0xbfb8aa3b, v77
	v_exp_f32_e32 v15, v15
	v_exp_f32_e32 v75, v75
	v_exp_f32_e32 v76, v76
	v_exp_f32_e32 v77, v77
	v_pk_mul_f32 v[66:67], v[66:67], v[106:107]
	s_waitcnt vmcnt(21)
; DI unsigned pk2(float lo, float hi) { f32x2 v = {lo, hi}; bf16x2_t b = __builtin_convertvector(v, bf16x2_t); return __builtin_bit_cast(unsigned, b); }
; DI float bflo(unsigned u) { return __uint_as_float(u << 16); }
; DI float bfhi(unsigned u) { return __uint_as_float(u & 0xffff0000u); }
; DI float sigmoidf_(float x) { return __builtin_amdgcn_rcpf(1.f + fexp(-x)); }
; DI void phase_m_out(int wv, const ArgP a, LAS unsigned char* lds, int dry) {
;     ...
; #pragma unroll
;         for (int tb = 0; tb < 2; ++tb) { bf16_t* op = QOK + (t0 + 32 * tb + r32) * 2048 + 512 + h * 256 + 32 * w;
; #pragma unroll
;             for (int p = 0; p < 2; ++p) {
;                 unsigned pk[2][2];
; #pragma unroll
;                 for (int q = 0; q < 2; ++q) { const int g = 2 * p + q, dv = 8 * g + 4 * hi; const u32x2 ov = *(const u32x2*)(op + dv);
;                     const f32x4 gg = *(const f32x4*)(ong + h * 256 + 32 * w + dv);
;                     const float og[4] = {bflo(ov.x), bfhi(ov.x), bflo(ov.y), bfhi(ov.y)}; float y[4];
; #pragma unroll
;                     for (int j = 0; j < 4; ++j) { const float hv = (tb ? acc1[4 * g + j] : acc0[4 * g + j]) * rn[tb]; y[j] = hv * gg[j] * sigmoidf_(og[j]); }
;                     pk[q][0] = pk2(y[0], y[1]); pk[q][1] = pk2(y[2], y[3]); }
;                 const auto r0 = __builtin_amdgcn_permlane32_swap(pk[0][0], pk[1][0], false, false), r1 = __builtin_amdgcn_permlane32_swap(pk[0][1], pk[1][1], false, false);
;                 if (!dry) *(u32x4*)(op + 16 * p + 8 * hi) = (u32x4){r0[0], r1[0], r0[1], r1[1]}; } }
	v_lshlrev_b32_e32 v78, 16, v110
	v_and_b32_e32 v79, 0xffff0000, v110
	v_mul_f32_e32 v78, 0xbfb8aa3b, v78
	v_lshlrev_b32_e32 v86, 16, v111
	v_and_b32_e32 v87, 0xffff0000, v111
	v_mul_f32_e32 v88, 0xbfb8aa3b, v79
	v_exp_f32_e32 v89, v78
	v_add_f32_e32 v15, 1.0, v15
	v_add_f32_e32 v75, 1.0, v75
	v_add_f32_e32 v78, 1.0, v76
	v_add_f32_e32 v79, 1.0, v77
	v_rcp_f32_e32 v76, v15
	v_rcp_f32_e32 v77, v75
	v_rcp_f32_e32 v78, v78
	v_rcp_f32_e32 v79, v79
	v_exp_f32_e32 v15, v88
	v_pk_mul_f32 v[64:65], v[64:65], v[76:77]
	v_add_f32_e32 v75, 1.0, v89
	v_pk_mul_f32 v[66:67], v[66:67], v[78:79]
	v_add_f32_e32 v15, 1.0, v15
	v_cvt_pk_bf16_f32 v64, v64, v65
	v_cvt_pk_bf16_f32 v65, v66, v67
	v_rcp_f32_e32 v67, v15
	v_mul_f32_e32 v15, 0xbfb8aa3b, v86
	v_rcp_f32_e32 v66, v75
	v_exp_f32_e32 v15, v15
	v_mul_f32_e32 v75, 0xbfb8aa3b, v87
	v_exp_f32_e32 v75, v75
	s_waitcnt vmcnt(20)
	v_pk_mul_f32 v[62:63], v[62:63], v[112:113]
	v_add_f32_e32 v15, 1.0, v15
	v_rcp_f32_e32 v76, v15
	v_add_f32_e32 v15, 1.0, v75
	v_rcp_f32_e32 v77, v15
	v_pk_mul_f32 v[60:61], v[60:61], v[114:115]
	v_pk_mul_f32 v[62:63], v[62:63], v[66:67]
	s_waitcnt vmcnt(19)
	v_lshlrev_b32_e32 v15, 16, v116
	v_pk_mul_f32 v[60:61], v[60:61], v[76:77]
	v_cvt_pk_bf16_f32 v66, v62, v63
	v_cvt_pk_bf16_f32 v67, v60, v61
	s_nop 0
	v_permlane32_swap_b32_e32 v64, v66
	v_permlane32_swap_b32_e32 v65, v67
	global_store_dwordx4 v[28:29], v[64:67], off offset:1024
	s_nop 0
	v_lshl_add_u64 v[76:77], v[30:31], 0, v[56:57]
	v_and_b32_e32 v57, 0xffff0000, v116
	v_lshlrev_b32_e32 v75, 16, v117
	v_and_b32_e32 v82, 0xffff0000, v117
	s_waitcnt vmcnt(19)
	v_lshlrev_b32_e32 v83, 16, v118
	v_and_b32_e32 v84, 0xffff0000, v118
	v_lshlrev_b32_e32 v86, 16, v119
	v_and_b32_e32 v85, 0xffff0000, v119
	v_mul_f32_e32 v15, 0xbfb8aa3b, v15
	v_mul_f32_e32 v57, 0xbfb8aa3b, v57
	v_mul_f32_e32 v75, 0xbfb8aa3b, v75
	v_mul_f32_e32 v82, 0xbfb8aa3b, v82
	v_mul_f32_e32 v83, 0xbfb8aa3b, v83
	v_mul_f32_e32 v84, 0xbfb8aa3b, v84
	v_mul_f32_e32 v86, 0xbfb8aa3b, v86
	v_mul_f32_e32 v85, 0xbfb8aa3b, v85
	v_exp_f32_e32 v15, v15
	v_exp_f32_e32 v57, v57
	v_exp_f32_e32 v75, v75
	v_exp_f32_e32 v82, v82
	v_exp_f32_e32 v83, v83
	v_exp_f32_e32 v84, v84
	v_exp_f32_e32 v86, v86
	v_exp_f32_e32 v85, v85
	v_add_f32_e32 v15, 1.0, v15
	v_add_f32_e32 v57, 1.0, v57
	v_add_f32_e32 v75, 1.0, v75
	v_add_f32_e32 v87, 1.0, v82
	v_add_f32_e32 v88, 1.0, v83
	v_add_f32_e32 v89, 1.0, v84
	v_add_f32_e32 v90, 1.0, v86
	v_add_f32_e32 v91, 1.0, v85
	v_rcp_f32_e32 v82, v15
	v_rcp_f32_e32 v83, v57
	v_rcp_f32_e32 v84, v75
	v_rcp_f32_e32 v85, v87
	v_rcp_f32_e32 v86, v88
	v_rcp_f32_e32 v87, v89
	v_rcp_f32_e32 v88, v90
	v_rcp_f32_e32 v89, v91
	v_mul_f32_e32 v15, 0x4b800000, v14
	v_cndmask_b32_e32 v14, v14, v15, vcc
	v_rsq_f32_e32 v14, v14
	s_waitcnt vmcnt(18)
	v_pk_mul_f32 v[24:25], v[24:25], v[120:121]
	v_pk_mul_f32 v[26:27], v[26:27], v[122:123]
	s_waitcnt vmcnt(17)
	v_pk_mul_f32 v[10:11], v[10:11], v[124:125]
	v_pk_mul_f32 v[12:13], v[12:13], v[126:127]
	v_pk_mul_f32 v[24:25], v[24:25], v[82:83]
	v_pk_mul_f32 v[26:27], v[26:27], v[84:85]
	v_pk_mul_f32 v[60:61], v[10:11], v[86:87]
	v_pk_mul_f32 v[62:63], v[12:13], v[88:89]
	v_cvt_pk_bf16_f32 v10, v24, v25
	v_cvt_pk_bf16_f32 v11, v26, v27
	v_cvt_pk_bf16_f32 v12, v60, v61
	v_cvt_pk_bf16_f32 v13, v62, v63
	s_nop 0
	v_permlane32_swap_b32_e32 v10, v12
	v_permlane32_swap_b32_e32 v11, v13
	global_store_dwordx4 v[28:29], v[10:13], off offset:1056
	s_nop 0
	v_mul_f32_e32 v15, 0x45800000, v14
	v_cndmask_b32_e32 v62, v14, v15, vcc
	v_pk_mul_f32 v[14:15], v[16:17], v[62:63] op_sel_hi:[1,0]
	v_pk_mul_f32 v[16:17], v[18:19], v[62:63] op_sel_hi:[1,0]
	v_pk_mul_f32 v[18:19], v[20:21], v[62:63] op_sel_hi:[1,0]
	v_pk_mul_f32 v[20:21], v[22:23], v[62:63] op_sel_hi:[1,0]
	v_lshl_add_u64 v[28:29], v[30:31], 0, v[36:37]
	s_waitcnt vmcnt(17)
	v_lshlrev_b32_e32 v22, 16, v128
	v_and_b32_e32 v23, 0xffff0000, v128
	v_lshlrev_b32_e32 v57, 16, v129
	v_and_b32_e32 v63, 0xffff0000, v129
	s_waitcnt vmcnt(16)
	v_lshlrev_b32_e32 v64, 16, v130
	v_and_b32_e32 v65, 0xffff0000, v130
	v_lshlrev_b32_e32 v66, 16, v131
	v_and_b32_e32 v67, 0xffff0000, v131
	v_mul_f32_e32 v22, 0xbfb8aa3b, v22
	v_mul_f32_e32 v23, 0xbfb8aa3b, v23
	v_mul_f32_e32 v57, 0xbfb8aa3b, v57
	v_mul_f32_e32 v63, 0xbfb8aa3b, v63
	v_mul_f32_e32 v64, 0xbfb8aa3b, v64
	v_mul_f32_e32 v65, 0xbfb8aa3b, v65
	v_mul_f32_e32 v66, 0xbfb8aa3b, v66
	v_mul_f32_e32 v67, 0xbfb8aa3b, v67
	v_exp_f32_e32 v22, v22
	v_exp_f32_e32 v23, v23
	v_exp_f32_e32 v57, v57
	v_exp_f32_e32 v63, v63
	v_exp_f32_e32 v64, v64
	v_exp_f32_e32 v65, v65
	v_exp_f32_e32 v66, v66
	v_exp_f32_e32 v67, v67
	v_add_f32_e32 v22, 1.0, v22
	v_add_f32_e32 v23, 1.0, v23
	v_add_f32_e32 v57, 1.0, v57
	v_add_f32_e32 v63, 1.0, v63
	v_add_f32_e32 v75, 1.0, v64
	v_add_f32_e32 v76, 1.0, v65
	v_add_f32_e32 v77, 1.0, v66
	v_add_f32_e32 v78, 1.0, v67
	v_rcp_f32_e32 v22, v22
	v_rcp_f32_e32 v23, v23
	v_rcp_f32_e32 v64, v57
	v_rcp_f32_e32 v65, v63
	v_rcp_f32_e32 v66, v75
	v_rcp_f32_e32 v67, v76
	v_rcp_f32_e32 v76, v77
	v_rcp_f32_e32 v77, v78
	v_pk_mul_f32 v[0:1], v[0:1], v[62:63] op_sel_hi:[1,0]
	v_pk_mul_f32 v[2:3], v[2:3], v[62:63] op_sel_hi:[1,0]
	v_pk_mul_f32 v[4:5], v[4:5], v[62:63] op_sel_hi:[1,0]
	v_pk_mul_f32 v[6:7], v[6:7], v[62:63] op_sel_hi:[1,0]
	v_pk_mul_f32 v[10:11], v[14:15], v[104:105]
	v_pk_mul_f32 v[12:13], v[16:17], v[106:107]
	v_pk_mul_f32 v[14:15], v[18:19], v[112:113]
	v_pk_mul_f32 v[16:17], v[20:21], v[114:115]
	v_pk_mul_f32 v[10:11], v[10:11], v[22:23]
	v_pk_mul_f32 v[12:13], v[12:13], v[64:65]
	v_pk_mul_f32 v[14:15], v[14:15], v[66:67]
	v_pk_mul_f32 v[16:17], v[16:17], v[76:77]
	v_cvt_pk_bf16_f32 v10, v10, v11
	v_cvt_pk_bf16_f32 v11, v12, v13
	v_cvt_pk_bf16_f32 v12, v14, v15
	v_cvt_pk_bf16_f32 v13, v16, v17
	s_nop 0
	v_permlane32_swap_b32_e32 v10, v12
	v_permlane32_swap_b32_e32 v11, v13
	global_store_dwordx4 v[28:29], v[10:13], off
	s_nop 0
	s_waitcnt vmcnt(16)
; #define LAS __attribute__((address_space(3)))
; DI unsigned pk2(float lo, float hi) { f32x2 v = {lo, hi}; bf16x2_t b = __builtin_convertvector(v, bf16x2_t); return __builtin_bit_cast(unsigned, b); }
; DI float bflo(unsigned u) { return __uint_as_float(u << 16); }
; DI float bfhi(unsigned u) { return __uint_as_float(u & 0xffff0000u); }
; DI void phase_m_out(int wv, const ArgP a, LAS unsigned char* lds, int dry) {
;     ...
;     for (int u = blockIdx.x; u < 1024; u += gridDim.x) {
;         const int c = u >> 2, h = u & 3; const size_t t0 = (size_t)c * 64;
;         for (int e = tid; e < 1024; e += 512) { const int r = e >> 4, p = e & 15;
;             *(LAS u32x4*)(Qs + r * MC_QROW + p * 16) = *(const u32x4*)(QOK + (t0 + r) * 2048 + h * 128 + p * 8);
;             *(LAS u32x4*)(Ks + r * MC_QROW + p * 16) = *(const u32x4*)(QOK + (t0 + r) * 2048 + 1536 + h * 128 + p * 8); }
;         if (tid < 64) { const float mstv = MST[c * 4 + h]; const float b = GB[(size_t)h * S + t0 + tid], e = GE[(size_t)h * S + t0 + tid], pm = GPM[(size_t)h * S + t0 + tid];
;             const float m = b + fmaxf(mstv, pm); f_b[tid] = b; f_e[tid] = e; f_m[tid] = m; f_g[tid] = fexp(b + mstv - m); }
;         if (tid >= 64 && tid < 192) f_n[tid - 64] = NST[(size_t)(c * 4 + h) * 128 + tid - 64];
;     ...
; #pragma unroll
;         for (int tb = 0; tb < 2; ++tb) { bf16_t* op = QOK + (t0 + 32 * tb + r32) * 2048 + 512 + h * 256 + 32 * w;
; #pragma unroll
;             for (int p = 0; p < 2; ++p) {
;                 unsigned pk[2][2];
; #pragma unroll
;                 for (int q = 0; q < 2; ++q) { const int g = 2 * p + q, dv = 8 * g + 4 * hi; const u32x2 ov = *(const u32x2*)(op + dv);
;                     const f32x4 gg = *(const f32x4*)(ong + h * 256 + 32 * w + dv);
;                     const float og[4] = {bflo(ov.x), bfhi(ov.x), bflo(ov.y), bfhi(ov.y)}; float y[4];
; #pragma unroll
;                     for (int j = 0; j < 4; ++j) { const float hv = (tb ? acc1[4 * g + j] : acc0[4 * g + j]) * rn[tb]; y[j] = hv * gg[j] * sigmoidf_(og[j]); }
;                     pk[q][0] = pk2(y[0], y[1]); pk[q][1] = pk2(y[2], y[3]); }
;                 const auto r0 = __builtin_amdgcn_permlane32_swap(pk[0][0], pk[1][0], false, false), r1 = __builtin_amdgcn_permlane32_swap(pk[0][1], pk[1][1], false, false);
;                 if (!dry) *(u32x4*)(op + 16 * p + 8 * hi) = (u32x4){r0[0], r1[0], r0[1], r1[1]}; } }
	v_lshlrev_b32_e32 v8, 16, v132
	v_and_b32_e32 v9, 0xffff0000, v132
	v_lshlrev_b32_e32 v18, 16, v133
	v_and_b32_e32 v19, 0xffff0000, v133
	s_waitcnt vmcnt(15)
	v_lshlrev_b32_e32 v20, 16, v134
	v_and_b32_e32 v21, 0xffff0000, v134
	v_lshlrev_b32_e32 v22, 16, v135
	v_and_b32_e32 v23, 0xffff0000, v135
	v_mul_f32_e32 v8, 0xbfb8aa3b, v8
	v_mul_f32_e32 v9, 0xbfb8aa3b, v9
	v_mul_f32_e32 v18, 0xbfb8aa3b, v18
	v_mul_f32_e32 v19, 0xbfb8aa3b, v19
	v_mul_f32_e32 v20, 0xbfb8aa3b, v20
	v_mul_f32_e32 v21, 0xbfb8aa3b, v21
	v_mul_f32_e32 v22, 0xbfb8aa3b, v22
	v_mul_f32_e32 v23, 0xbfb8aa3b, v23
	v_exp_f32_e32 v8, v8
	v_exp_f32_e32 v9, v9
	v_exp_f32_e32 v18, v18
	v_exp_f32_e32 v19, v19
	v_exp_f32_e32 v20, v20
	v_exp_f32_e32 v21, v21
	v_exp_f32_e32 v22, v22
	v_exp_f32_e32 v23, v23
	v_add_f32_e32 v8, 1.0, v8
	v_add_f32_e32 v9, 1.0, v9
	v_add_f32_e32 v18, 1.0, v18
	v_add_f32_e32 v19, 1.0, v19
	v_add_f32_e32 v20, 1.0, v20
	v_add_f32_e32 v21, 1.0, v21
	v_add_f32_e32 v22, 1.0, v22
	v_add_f32_e32 v23, 1.0, v23
	v_rcp_f32_e32 v8, v8
	v_rcp_f32_e32 v9, v9
	v_rcp_f32_e32 v18, v18
	v_rcp_f32_e32 v19, v19
	v_rcp_f32_e32 v20, v20
	v_rcp_f32_e32 v21, v21
	v_rcp_f32_e32 v22, v22
	v_rcp_f32_e32 v23, v23
	v_pk_mul_f32 v[0:1], v[0:1], v[120:121]
	v_pk_mul_f32 v[2:3], v[2:3], v[122:123]
	v_pk_mul_f32 v[4:5], v[4:5], v[124:125]
	v_pk_mul_f32 v[6:7], v[6:7], v[126:127]
	v_pk_mul_f32 v[0:1], v[0:1], v[8:9]
	v_pk_mul_f32 v[2:3], v[2:3], v[18:19]
	v_pk_mul_f32 v[4:5], v[4:5], v[20:21]
	v_pk_mul_f32 v[6:7], v[6:7], v[22:23]
	v_cvt_pk_bf16_f32 v0, v0, v1
	v_cvt_pk_bf16_f32 v1, v2, v3
	v_cvt_pk_bf16_f32 v2, v4, v5
	v_cvt_pk_bf16_f32 v3, v6, v7
	s_nop 0
	v_permlane32_swap_b32_e32 v0, v2
	v_permlane32_swap_b32_e32 v1, v3
	global_store_dwordx4 v[28:29], v[0:3], off offset:32
	s_barrier
	s_cmpk_lt_i32 s66, 0x400
	s_cbranch_scc0 .LBB0_1653
.LBB0_1606:
	s_ashr_i32 s48, s66, 2
	s_ashr_i32 s49, s48, 31
	s_and_b32 s76, s66, 3
	s_lshl_b64 s[68:69], s[48:49], 6
	s_and_saveexec_b64 s[48:49], s[4:5]
	s_lshl_b32 s0, s76, 8
	v_lshl_add_u64 v[0:1], v[52:53], 0, s[0:1]
	v_ashrrev_i32_e32 v12, 4, v32
	v_add_u32_e32 v2, 0x200, v32
	v_ashrrev_i32_e32 v13, 31, v12
	v_ashrrev_i32_e32 v14, 4, v2
	v_ashrrev_i32_e32 v15, 31, v14
	v_lshl_add_u64 v[24:25], s[68:69], 0, v[12:13]
	v_lshl_add_u64 v[2:3], s[68:69], 0, v[14:15]
	v_lshlrev_b64 v[24:25], 12, v[24:25]
	v_lshlrev_b64 v[2:3], 12, v[2:3]
	v_lshl_add_u64 v[24:25], v[0:1], 0, v[24:25]
	v_lshl_add_u64 v[2:3], v[0:1], 0, v[2:3]
	global_load_dwordx4 v[4:7], v[24:25], off
	global_load_dwordx4 v[8:11], v[24:25], off offset:3072
	global_load_dwordx4 v[16:19], v[2:3], off
	global_load_dwordx4 v[20:23], v[2:3], off offset:3072
	v_mad_u64_u32 v[12:13], s[78:79], v12, s72, v[48:49]
	v_mad_u64_u32 v[14:15], s[78:79], v14, s72, v[48:49]
	s_or_b64 exec, exec, s[48:49]
	s_and_saveexec_b64 s[48:49], s[6:7]
	s_ashr_i32 s67, s66, 31
	s_lshl_b64 s[70:71], s[66:67], 2
	s_add_u32 s70, s33, s70
	s_addc_u32 s71, s63, s71
	s_lshl_b32 s0, s76, 14
	s_add_u32 s78, s68, s0
	s_addc_u32 s79, s69, 0
	v_lshl_add_u64 v[0:1], s[78:79], 0, v[32:33]
	v_lshlrev_b64 v[0:1], 2, v[0:1]
	v_lshl_add_u64 v[2:3], s[56:57], 0, v[0:1]
	global_load_dword v26, v37, s[70:71]
	global_load_dword v27, v[2:3], off
	v_lshl_add_u64 v[2:3], s[52:53], 0, v[0:1]
	global_load_dword v28, v[2:3], off
	v_lshl_add_u64 v[0:1], s[54:55], 0, v[0:1]
	global_load_dword v29, v[0:1], off
	s_or_b64 exec, exec, s[48:49]
	s_and_saveexec_b64 s[48:49], s[8:9]
	s_lshl_b64 s[78:79], s[66:67], 9
	v_lshl_add_u64 v[0:1], v[38:39], 0, s[78:79]
	global_load_dword v30, v[0:1], off
	s_or_b64 exec, exec, s[48:49]
	s_and_saveexec_b64 s[48:49], s[4:5]
	s_waitcnt vmcnt(5)
	ds_write_b128 v12, v[4:7]
	ds_write_b128 v12, v[8:11] offset:17408
	ds_write_b128 v14, v[16:19]
	ds_write_b128 v14, v[20:23] offset:17408
	s_or_b64 exec, exec, s[48:49]
	s_and_saveexec_b64 s[48:49], s[6:7]
	s_waitcnt vmcnt(1)
	v_max_f32_e32 v1, v26, v26
	v_max_f32_e32 v3, v27, v27
	v_max_f32_e32 v1, v1, v3
	v_add_f32_e32 v1, v28, v1
	v_add_f32_e32 v3, v26, v28
	v_sub_f32_e32 v3, v3, v1
	v_mul_f32_e32 v3, 0x3fb8aa3b, v3
	v_exp_f32_e32 v3, v3
	s_nop 0
	ds_write2st64_b32 v43, v28, v29 offset0:172 offset1:173
	ds_write2st64_b32 v43, v1, v3 offset0:174 offset1:175
	s_or_b64 exec, exec, s[48:49]
	s_and_saveexec_b64 s[48:49], s[8:9]
	s_waitcnt vmcnt(0)
	ds_write_b32 v43, v30 offset:46080
